# baseline (speedup 1.0000x reference)
; static __device__ __forceinline__ void attn_item(const Params& p, int head, int j, char* smraw) {
;     ...
;     for (int qt = 0; qt < 2; ++qt) {
;       float ps = 0.f;
; #pragma unroll
;       for (int kt = 0; kt < 4; ++kt)
; #pragma unroll
;         for (int r = 0; r < 4; ++r) {
;           const float pv = __builtin_amdgcn_exp2f(sacc[kt][qt][r]);
;           sacc[kt][qt][r] = pv; ps += pv;
;         }
;       lrun[qt] += ps;
.LBB0_375:
	s_add_i32 s3, s3, 2
	v_lshl_add_u64 v[134:135], v[134:135], 0, s[8:9]
	v_lshl_add_u64 v[136:137], v[136:137], 0, s[8:9]
	v_lshl_add_u64 v[138:139], v[138:139], 0, s[10:11]
	v_lshl_add_u64 v[140:141], v[140:141], 0, s[10:11]
	s_cmp_lt_u32 s12, s2
	v_lshl_add_u64 v[142:143], v[142:143], 0, s[10:11]
	s_waitcnt lgkmcnt(0)
	s_barrier
	s_cbranch_scc0 .LBB0_367

; #define MFMA16(a, b, c) __builtin_amdgcn_mfma_f32_16x16x32_bf16((a), (b), (c), 0, 0, 0)
; static __device__ __forceinline__ void attn_item(const Params& p, int head, int j, char* smraw) {
;     ...
;     bf16x8 pf[2][2];
; #pragma unroll
;     for (int qt = 0; qt < 2; ++qt) {
;       float ps = 0.f;
; #pragma unroll
;       for (int kt = 0; kt < 4; ++kt)
; #pragma unroll
;         for (int r = 0; r < 4; ++r) {
;           const float pv = __builtin_amdgcn_exp2f(sacc[kt][qt][r]);
;           sacc[kt][qt][r] = pv; ps += pv;
;         }
;       lrun[qt] += ps;
; #pragma unroll
;       for (int k2 = 0; k2 < 2; ++k2) {
;         u32x4 pk = {cvtpk(sacc[2 * k2][qt][0], sacc[2 * k2][qt][1]), cvtpk(sacc[2 * k2][qt][2], sacc[2 * k2][qt][3]),
;                     cvtpk(sacc[2 * k2 + 1][qt][0], sacc[2 * k2 + 1][qt][1]), cvtpk(sacc[2 * k2 + 1][qt][2], sacc[2 * k2 + 1][qt][3])};
;         pf[qt][k2] = *(bf16x8*)&pk;
;       }
;     }
;     {
;       bf16x8 vf[2][4];
; #pragma unroll
;       for (int k2 = 0; k2 < 2; ++k2)
; #pragma unroll
;         for (int dt = 0; dt < 4; ++dt) vf[k2][dt] = *(const bf16x8*)(cV + (dt * 16 + l15) * 64 + (((k2 * 4 + quad) ^ (l15 & 7)) << 3));
;       __builtin_amdgcn_sched_barrier(0);
;       __builtin_amdgcn_s_setprio(1);
; #pragma unroll
;       for (int k2 = 0; k2 < 2; ++k2)
; #pragma unroll
;         for (int dt = 0; dt < 4; ++dt)
; #pragma unroll
;           for (int qt = 0; qt < 2; ++qt) oacc[dt][qt] = MFMA16(vf[k2][dt], pf[qt][k2], oacc[dt][qt]);
;       __builtin_amdgcn_s_setprio(0);
;       __builtin_amdgcn_sched_barrier(0);
;     }
.LBB0_380:
	v_exp_f32_e32 v173, v124
	v_exp_f32_e32 v169, v126
	v_exp_f32_e32 v161, v122
	v_exp_f32_e32 v172, v108
	v_exp_f32_e32 v170, v109
	v_exp_f32_e32 v168, v110
	v_exp_f32_e32 v166, v111
	v_exp_f32_e32 v164, v104
	v_exp_f32_e32 v162, v105
	v_exp_f32_e32 v160, v106
	v_exp_f32_e32 v158, v107
	v_exp_f32_e32 v156, v100
	v_exp_f32_e32 v126, v101
	v_exp_f32_e32 v124, v102
	v_exp_f32_e32 v122, v103
	ds_read_b128 v[100:103], v187 offset:16384
	ds_read_b128 v[104:107], v187 offset:18432
	ds_read_b128 v[108:111], v187 offset:20480
	ds_read_b128 v[200:203], v187 offset:22528
	ds_read_b128 v[204:207], v188 offset:16384
	ds_read_b128 v[208:211], v188 offset:18432
	ds_read_b128 v[212:215], v188 offset:20480
	ds_read_b128 v[216:219], v188 offset:22528
	v_exp_f32_e32 v171, v125
	v_exp_f32_e32 v167, v127
	v_exp_f32_e32 v165, v120
	v_exp_f32_e32 v163, v121
	v_exp_f32_e32 v159, v123
	v_exp_f32_e32 v157, v116
	v_exp_f32_e32 v127, v117
	v_exp_f32_e32 v125, v118
	v_exp_f32_e32 v123, v119
	v_exp_f32_e32 v121, v112
	v_exp_f32_e32 v119, v113
	v_exp_f32_e32 v117, v114
	v_exp_f32_e32 v113, v115
	v_exp_f32_e32 v120, v96
	v_exp_f32_e32 v118, v97
	v_exp_f32_e32 v116, v98
	v_exp_f32_e32 v112, v99
	v_cvt_pk_bf16_f32 v192, v173, v171
	v_cvt_pk_bf16_f32 v193, v169, v167
	v_cvt_pk_bf16_f32 v194, v165, v163
	v_cvt_pk_bf16_f32 v195, v161, v159
	v_cvt_pk_bf16_f32 v196, v157, v127
	v_cvt_pk_bf16_f32 v197, v125, v123
	v_cvt_pk_bf16_f32 v198, v121, v119
	v_cvt_pk_bf16_f32 v199, v117, v113
	v_cvt_pk_bf16_f32 v96, v172, v170
	v_cvt_pk_bf16_f32 v97, v168, v166
	v_cvt_pk_bf16_f32 v98, v164, v162
	v_cvt_pk_bf16_f32 v99, v160, v158
	v_cvt_pk_bf16_f32 v220, v156, v126
	v_cvt_pk_bf16_f32 v221, v124, v122
	v_cvt_pk_bf16_f32 v222, v120, v118
	v_cvt_pk_bf16_f32 v223, v116, v112
	s_setprio 1
	s_waitcnt lgkmcnt(7)
	v_mfma_f32_16x16x32_bf16 v[92:95], v[100:103], v[192:195], v[92:95]
	v_add_f32_e32 v226, 0, v172
	v_add_f32_e32 v227, 0, v173
	v_mfma_f32_16x16x32_bf16 v[76:79], v[100:103], v[96:99], v[76:79]
	v_add_f32_e32 v226, v170, v226
	v_add_f32_e32 v227, v171, v227
	s_waitcnt lgkmcnt(6)
	v_mfma_f32_16x16x32_bf16 v[100:103], v[104:107], v[192:195], v[88:91]
	v_add_f32_e32 v226, v168, v226
	v_add_f32_e32 v227, v169, v227
	v_mfma_f32_16x16x32_bf16 v[72:75], v[104:107], v[96:99], v[72:75]
	v_add_f32_e32 v226, v166, v226
	v_add_f32_e32 v227, v167, v227
	s_waitcnt lgkmcnt(5)
	v_mfma_f32_16x16x32_bf16 v[104:107], v[108:111], v[192:195], v[84:87]
	v_add_f32_e32 v226, v164, v226
	v_add_f32_e32 v227, v165, v227
	v_mfma_f32_16x16x32_bf16 v[68:71], v[108:111], v[96:99], v[68:71]
	v_add_f32_e32 v226, v162, v226
	v_add_f32_e32 v227, v163, v227
	s_waitcnt lgkmcnt(4)
	v_mfma_f32_16x16x32_bf16 v[108:111], v[200:203], v[192:195], v[80:83]
	v_add_f32_e32 v226, v160, v226
	v_add_f32_e32 v227, v161, v227
	v_mfma_f32_16x16x32_bf16 v[64:67], v[200:203], v[96:99], v[64:67]
	v_add_f32_e32 v226, v158, v226
	v_add_f32_e32 v227, v159, v227
	s_waitcnt lgkmcnt(3)
	v_mfma_f32_16x16x32_bf16 v[92:95], v[204:207], v[196:199], v[92:95]
	v_add_f32_e32 v226, v156, v226
	v_add_f32_e32 v227, v157, v227
	v_mfma_f32_16x16x32_bf16 v[88:91], v[204:207], v[220:223], v[76:79]
	v_add_f32_e32 v226, v126, v226
	v_add_f32_e32 v227, v127, v227
	s_waitcnt lgkmcnt(2)
	v_mfma_f32_16x16x32_bf16 v[84:87], v[208:211], v[196:199], v[100:103]
	v_add_f32_e32 v226, v124, v226
	v_add_f32_e32 v227, v125, v227
	v_mfma_f32_16x16x32_bf16 v[80:83], v[208:211], v[220:223], v[72:75]
	v_add_f32_e32 v226, v122, v226
	v_add_f32_e32 v227, v123, v227
	s_waitcnt lgkmcnt(1)
	v_mfma_f32_16x16x32_bf16 v[76:79], v[212:215], v[196:199], v[104:107]
	v_add_f32_e32 v226, v120, v226
	v_add_f32_e32 v227, v121, v227
	v_mfma_f32_16x16x32_bf16 v[72:75], v[212:215], v[220:223], v[68:71]
	v_add_f32_e32 v226, v118, v226
	v_add_f32_e32 v227, v119, v227
	s_waitcnt lgkmcnt(0)
	v_mfma_f32_16x16x32_bf16 v[68:71], v[216:219], v[196:199], v[108:111]
	v_add_f32_e32 v226, v116, v226
	v_add_f32_e32 v227, v117, v227
	v_mfma_f32_16x16x32_bf16 v[64:67], v[216:219], v[220:223], v[64:67]
	v_add_f32_e32 v226, v112, v226
	v_add_f32_e32 v227, v113, v227
	s_setprio 0
	v_pk_add_f32 v[144:145], v[144:145], v[226:227]
	s_cmp_ge_u32 s3, s2
	s_waitcnt vmcnt(4)
	ds_write_b128 v179, v[44:47] offset:24576
	s_waitcnt vmcnt(3)
	ds_write_b128 v180, v[48:51] offset:24576
	s_waitcnt vmcnt(2)
	ds_write_b128 v181, v[52:55] offset:24576
	s_waitcnt vmcnt(1)
	ds_write_b128 v182, v[56:59] offset:40960
	s_waitcnt vmcnt(0)
	ds_write_b128 v183, v[60:63] offset:40960
	s_waitcnt lgkmcnt(0)
	s_barrier
	s_cbranch_scc1 .LBB0_382
	v_lshl_add_u64 v[44:45], v[142:143], 0, s[98:99]
	v_lshl_add_u64 v[48:49], v[140:141], 0, s[98:99]
	v_lshl_add_u64 v[52:53], v[138:139], 0, s[98:99]
	global_load_dwordx4 v[44:47], v[44:45], off
	s_nop 0
	global_load_dwordx4 v[48:51], v[48:49], off
	s_nop 0
	global_load_dwordx4 v[52:55], v[52:53], off
	global_load_dwordx4 v[56:59], v[134:135], off offset:384
	global_load_dwordx4 v[60:63], v[136:137], off offset:384
; #define MFMA16(a, b, c) __builtin_amdgcn_mfma_f32_16x16x32_bf16((a), (b), (c), 0, 0, 0)
; static __device__ __forceinline__ void attn_item(const Params& p, int head, int j, char* smraw) {
;     ...
;     f32x4 sacc[4][2];
; #pragma unroll
;     for (int b = 0; b < 2; ++b) {
;       const float mi = -mrun[b];
; #pragma unroll
;       for (int a = 0; a < 4; ++a) sacc[a][b] = f32x4{mi, mi, mi, mi};
;     }
;     {
;       bf16x8 kf[3][4];
; #pragma unroll
;       for (int ks = 0; ks < 3; ++ks)
; #pragma unroll
;         for (int kt = 0; kt < 4; ++kt) kf[ks][kt] = *(const bf16x8*)(cK + (kt * 16 + l15) * 128 + (((ks * 4 + quad) ^ l15) << 3));
;       __builtin_amdgcn_sched_barrier(0);
;       __builtin_amdgcn_s_setprio(1);
; #pragma unroll
;       for (int ks = 0; ks < 3; ++ks)
; #pragma unroll
;         for (int kt = 0; kt < 4; ++kt)
; #pragma unroll
;           for (int qt = 0; qt < 2; ++qt) sacc[kt][qt] = MFMA16(kf[ks][kt], qf[qt][ks], sacc[kt][qt]);
;       __builtin_amdgcn_s_setprio(0);
;       __builtin_amdgcn_sched_barrier(0);
;     }
;     float mx[2];
; #pragma unroll
;     for (int qt = 0; qt < 2; ++qt) {
;       float m = sacc[0][qt][0];
; #pragma unroll
;       for (int kt = 0; kt < 4; ++kt)
; #pragma unroll
;         for (int r = 0; r < 4; ++r) m = fmaxf(m, sacc[kt][qt][r]);
;       mx[qt] = max_x16_x32(m);
;     }
;     if (__any(first || mx[0] > THR || mx[1] > THR)) {
; #pragma unroll
;       for (int qt = 0; qt < 2; ++qt) {
;         const float d = first ? mx[qt] : fmaxf(mx[qt], 0.f);
;         const float alpha = first ? 1.f : __builtin_amdgcn_exp2f(-d);
;         mrun[qt] += d;
;         lrun[qt] *= alpha;
; #pragma unroll
;         for (int dt = 0; dt < 4; ++dt) oacc[dt][qt] = oacc[dt][qt] * alpha;
; #pragma unroll
;         for (int kt = 0; kt < 4; ++kt)
; #pragma unroll
;           for (int r = 0; r < 4; ++r) sacc[kt][qt][r] -= d;
;       }
;     ...
;     for (int qt = 0; qt < 2; ++qt) {
;       float ps = 0.f;
; #pragma unroll
;       for (int kt = 0; kt < 4; ++kt)
; #pragma unroll
;         for (int r = 0; r < 4; ++r) {
;           const float pv = __builtin_amdgcn_exp2f(sacc[kt][qt][r]);
;           sacc[kt][qt][r] = pv; ps += pv;
;         }
;       lrun[qt] += ps;
.LBB0_382:
	v_xor_b32_e32 v166, 0x80000000, v189
	v_mov_b32_e32 v167, v166
	v_mov_b32_e32 v168, v166
	v_mov_b32_e32 v169, v166
	ds_read_b128 v[100:103], v184 offset:24576
	ds_read_b128 v[104:107], v184 offset:28672
	ds_read_b128 v[108:111], v184 offset:32768
	ds_read_b128 v[112:115], v184 offset:36864
	ds_read_b128 v[116:119], v185 offset:24576
	ds_read_b128 v[120:123], v185 offset:28672
	ds_read_b128 v[124:127], v185 offset:32768
	ds_read_b128 v[146:149], v185 offset:36864
	ds_read_b128 v[150:153], v186 offset:24576
	ds_read_b128 v[154:157], v186 offset:28672
	ds_read_b128 v[158:161], v186 offset:32768
	ds_read_b128 v[162:165], v186 offset:36864
	v_xor_b32_e32 v96, 0x80000000, v190
	v_mov_b32_e32 v97, v96
	v_mov_b32_e32 v98, v96
	v_mov_b32_e32 v99, v96
	s_setprio 1
	s_waitcnt lgkmcnt(11)
	v_mfma_f32_16x16x32_bf16 v[170:173], v[100:103], v[0:3], v[96:99]
	v_mfma_f32_16x16x32_bf16 v[100:103], v[100:103], v[12:15], v[166:169]
	s_waitcnt lgkmcnt(10)
	v_mfma_f32_16x16x32_bf16 v[192:195], v[104:107], v[0:3], v[96:99]
	v_mfma_f32_16x16x32_bf16 v[104:107], v[104:107], v[12:15], v[166:169]
	s_waitcnt lgkmcnt(9)
	v_mfma_f32_16x16x32_bf16 v[196:199], v[108:111], v[0:3], v[96:99]
	v_mfma_f32_16x16x32_bf16 v[108:111], v[108:111], v[12:15], v[166:169]
	s_waitcnt lgkmcnt(8)
	v_mfma_f32_16x16x32_bf16 v[96:99], v[112:115], v[0:3], v[96:99]
	v_mfma_f32_16x16x32_bf16 v[112:115], v[112:115], v[12:15], v[166:169]
	s_waitcnt lgkmcnt(7)
	v_mfma_f32_16x16x32_bf16 v[166:169], v[116:119], v[4:7], v[170:173]
	v_mfma_f32_16x16x32_bf16 v[100:103], v[116:119], v[16:19], v[100:103]
	s_waitcnt lgkmcnt(6)
	v_mfma_f32_16x16x32_bf16 v[116:119], v[120:123], v[4:7], v[192:195]
	v_mfma_f32_16x16x32_bf16 v[104:107], v[120:123], v[16:19], v[104:107]
	s_waitcnt lgkmcnt(5)
	v_mfma_f32_16x16x32_bf16 v[170:173], v[124:127], v[4:7], v[196:199]
	v_mfma_f32_16x16x32_bf16 v[192:195], v[124:127], v[16:19], v[108:111]
	s_waitcnt lgkmcnt(4)
	v_mfma_f32_16x16x32_bf16 v[96:99], v[146:149], v[4:7], v[96:99]
	v_mfma_f32_16x16x32_bf16 v[146:149], v[146:149], v[16:19], v[112:115]
	s_waitcnt lgkmcnt(3)
	v_mfma_f32_16x16x32_bf16 v[124:127], v[150:153], v[8:11], v[166:169]
	v_mfma_f32_16x16x32_bf16 v[108:111], v[150:153], v[20:23], v[100:103]
	s_waitcnt lgkmcnt(2)
	v_mfma_f32_16x16x32_bf16 v[120:123], v[154:157], v[8:11], v[116:119]
	v_mfma_f32_16x16x32_bf16 v[104:107], v[154:157], v[20:23], v[104:107]
	s_waitcnt lgkmcnt(1)
	v_mfma_f32_16x16x32_bf16 v[116:119], v[158:161], v[8:11], v[170:173]
	v_mfma_f32_16x16x32_bf16 v[100:103], v[158:161], v[20:23], v[192:195]
	s_waitcnt lgkmcnt(0)
	v_mfma_f32_16x16x32_bf16 v[112:115], v[162:165], v[8:11], v[96:99]
	v_mfma_f32_16x16x32_bf16 v[96:99], v[162:165], v[20:23], v[146:149]
	s_setprio 0
	v_max_f32_e32 v128, v125, v125
	s_nop 0
	v_max_f32_e32 v146, v124, v124
	v_max_f32_e32 v128, v146, v128
	v_max3_f32 v128, v128, v126, v127
	v_max3_f32 v128, v128, v120, v121
	v_max3_f32 v128, v128, v122, v123
	v_max3_f32 v128, v128, v116, v117
	v_max3_f32 v128, v128, v118, v119
	v_max3_f32 v128, v128, v112, v113
	v_max3_f32 v128, v128, v114, v115
	v_mov_b32_e32 v146, v128
	v_max_f32_e32 v128, v109, v109
	v_max_f32_e32 v147, v108, v108
	v_max_f32_e32 v128, v147, v128
	v_max3_f32 v128, v128, v110, v111
	v_max3_f32 v128, v128, v104, v105
	v_max3_f32 v128, v128, v106, v107
	v_max3_f32 v128, v128, v100, v101
	v_max3_f32 v128, v128, v102, v103
	v_max3_f32 v128, v128, v96, v97
	v_max3_f32 v128, v128, v98, v99
	v_max_f32_e32 v147, v146, v128
	v_cmp_lt_f32_e32 vcc, s33, v147
	s_cbranch_vccz .LBB0_384
	v_mov_b32_e32 v147, v146
	s_nop 1
	v_permlane16_swap_b32_e32 v146, v147
	v_max_f32_e32 v147, v147, v147
	v_max_f32_e32 v146, v146, v146
	v_max_f32_e32 v146, v146, v147
	v_mov_b32_e32 v147, v146
	s_nop 1
	v_permlane32_swap_b32_e32 v146, v147
	v_max_f32_e32 v147, v147, v147
	v_max_f32_e32 v146, v146, v146
	v_max_f32_e32 v146, v146, v147
	v_mov_b32_e32 v147, v128
	s_nop 1
	v_permlane16_swap_b32_e32 v128, v147
	v_max_f32_e32 v147, v147, v147
	v_max_f32_e32 v128, v128, v128
	v_max_f32_e32 v128, v128, v147
	v_mov_b32_e32 v147, v128
	s_nop 1
	v_permlane32_swap_b32_e32 v128, v147
	v_max_f32_e32 v147, v147, v147
	v_max_f32_e32 v128, v128, v128
	v_max_f32_e32 v128, v128, v147
	v_max_f32_e32 v146, v146, v146
	v_max_f32_e32 v146, 0, v146
	v_max_f32_e32 v128, v128, v128
	v_exp_f32_e64 v148, -v146
	v_max_f32_e32 v128, 0, v128
	v_exp_f32_e64 v150, -v128
	v_add_f32_e32 v190, v190, v146
	v_mov_b32_e32 v151, v148
	v_pk_mul_f32 v[94:95], v[94:95], v[148:149] op_sel_hi:[1,0]
	v_pk_mul_f32 v[92:93], v[92:93], v[148:149] op_sel_hi:[1,0]
	v_pk_mul_f32 v[86:87], v[86:87], v[148:149] op_sel_hi:[1,0]
	v_pk_mul_f32 v[84:85], v[84:85], v[148:149] op_sel_hi:[1,0]
	v_pk_mul_f32 v[78:79], v[78:79], v[148:149] op_sel_hi:[1,0]
	v_pk_mul_f32 v[76:77], v[76:77], v[148:149] op_sel_hi:[1,0]
	v_pk_mul_f32 v[70:71], v[70:71], v[148:149] op_sel_hi:[1,0]
	v_pk_mul_f32 v[68:69], v[68:69], v[148:149] op_sel_hi:[1,0]
	v_pk_add_f32 v[124:125], v[124:125], v[146:147] op_sel_hi:[1,0] neg_lo:[0,1] neg_hi:[0,1]
	v_pk_add_f32 v[126:127], v[126:127], v[146:147] op_sel_hi:[1,0] neg_lo:[0,1] neg_hi:[0,1]
	v_pk_add_f32 v[120:121], v[120:121], v[146:147] op_sel_hi:[1,0] neg_lo:[0,1] neg_hi:[0,1]
	v_pk_add_f32 v[122:123], v[122:123], v[146:147] op_sel_hi:[1,0] neg_lo:[0,1] neg_hi:[0,1]
	v_pk_add_f32 v[116:117], v[116:117], v[146:147] op_sel_hi:[1,0] neg_lo:[0,1] neg_hi:[0,1]
	v_pk_add_f32 v[118:119], v[118:119], v[146:147] op_sel_hi:[1,0] neg_lo:[0,1] neg_hi:[0,1]
	v_pk_add_f32 v[112:113], v[112:113], v[146:147] op_sel_hi:[1,0] neg_lo:[0,1] neg_hi:[0,1]
	v_pk_add_f32 v[114:115], v[114:115], v[146:147] op_sel_hi:[1,0] neg_lo:[0,1] neg_hi:[0,1]
	v_add_f32_e32 v189, v189, v128
	v_pk_mul_f32 v[144:145], v[144:145], v[150:151]
	v_pk_mul_f32 v[90:91], v[90:91], v[150:151] op_sel_hi:[1,0]
	v_pk_mul_f32 v[88:89], v[88:89], v[150:151] op_sel_hi:[1,0]
	v_pk_mul_f32 v[82:83], v[82:83], v[150:151] op_sel_hi:[1,0]
	v_pk_mul_f32 v[80:81], v[80:81], v[150:151] op_sel_hi:[1,0]
	v_pk_mul_f32 v[74:75], v[74:75], v[150:151] op_sel_hi:[1,0]
	v_pk_mul_f32 v[72:73], v[72:73], v[150:151] op_sel_hi:[1,0]
	v_pk_mul_f32 v[66:67], v[66:67], v[150:151] op_sel_hi:[1,0]
	v_pk_mul_f32 v[64:65], v[64:65], v[150:151] op_sel_hi:[1,0]
	v_pk_add_f32 v[108:109], v[108:109], v[128:129] op_sel_hi:[1,0] neg_lo:[0,1] neg_hi:[0,1]
	v_pk_add_f32 v[110:111], v[110:111], v[128:129] op_sel_hi:[1,0] neg_lo:[0,1] neg_hi:[0,1]
	v_pk_add_f32 v[104:105], v[104:105], v[128:129] op_sel_hi:[1,0] neg_lo:[0,1] neg_hi:[0,1]
	v_pk_add_f32 v[106:107], v[106:107], v[128:129] op_sel_hi:[1,0] neg_lo:[0,1] neg_hi:[0,1]
	v_pk_add_f32 v[100:101], v[100:101], v[128:129] op_sel_hi:[1,0] neg_lo:[0,1] neg_hi:[0,1]
	v_pk_add_f32 v[102:103], v[102:103], v[128:129] op_sel_hi:[1,0] neg_lo:[0,1] neg_hi:[0,1]
	v_pk_add_f32 v[96:97], v[96:97], v[128:129] op_sel_hi:[1,0] neg_lo:[0,1] neg_hi:[0,1]
	v_pk_add_f32 v[98:99], v[98:99], v[128:129] op_sel_hi:[1,0] neg_lo:[0,1] neg_hi:[0,1]
; #define MFMA16(a, b, c) __builtin_amdgcn_mfma_f32_16x16x32_bf16((a), (b), (c), 0, 0, 0)
; static __device__ __forceinline__ void attn_item(const Params& p, int head, int j, char* smraw) {
;     ...
;     bf16x8 pf[2][2];
; #pragma unroll
;     for (int qt = 0; qt < 2; ++qt) {
;       float ps = 0.f;
; #pragma unroll
;       for (int kt = 0; kt < 4; ++kt)
; #pragma unroll
;         for (int r = 0; r < 4; ++r) {
;           const float pv = __builtin_amdgcn_exp2f(sacc[kt][qt][r]);
;           sacc[kt][qt][r] = pv; ps += pv;
;         }
;       lrun[qt] += ps;
; #pragma unroll
;       for (int k2 = 0; k2 < 2; ++k2) {
;         u32x4 pk = {cvtpk(sacc[2 * k2][qt][0], sacc[2 * k2][qt][1]), cvtpk(sacc[2 * k2][qt][2], sacc[2 * k2][qt][3]),
;                     cvtpk(sacc[2 * k2 + 1][qt][0], sacc[2 * k2 + 1][qt][1]), cvtpk(sacc[2 * k2 + 1][qt][2], sacc[2 * k2 + 1][qt][3])};
;         pf[qt][k2] = *(bf16x8*)&pk;
;       }
;     }
;     {
;       bf16x8 vf[2][4];
; #pragma unroll
;       for (int k2 = 0; k2 < 2; ++k2)
; #pragma unroll
;         for (int dt = 0; dt < 4; ++dt) vf[k2][dt] = *(const bf16x8*)(cV + (dt * 16 + l15) * 64 + (((k2 * 4 + quad) ^ (l15 & 7)) << 3));
;       __builtin_amdgcn_sched_barrier(0);
;       __builtin_amdgcn_s_setprio(1);
; #pragma unroll
;       for (int k2 = 0; k2 < 2; ++k2)
; #pragma unroll
;         for (int dt = 0; dt < 4; ++dt)
; #pragma unroll
;           for (int qt = 0; qt < 2; ++qt) oacc[dt][qt] = MFMA16(vf[k2][dt], pf[qt][k2], oacc[dt][qt]);
;       __builtin_amdgcn_s_setprio(0);
;       __builtin_amdgcn_sched_barrier(0);
;     }
.LBB0_384:
	v_exp_f32_e32 v163, v124
	v_exp_f32_e32 v159, v126
	v_exp_f32_e32 v151, v122
	v_exp_f32_e32 v162, v108
	v_exp_f32_e32 v160, v109
	v_exp_f32_e32 v158, v110
	v_exp_f32_e32 v156, v111
	v_exp_f32_e32 v154, v104
	v_exp_f32_e32 v152, v105
	v_exp_f32_e32 v150, v106
	v_exp_f32_e32 v148, v107
	v_exp_f32_e32 v146, v100
	v_exp_f32_e32 v126, v101
	v_exp_f32_e32 v124, v102
	v_exp_f32_e32 v122, v103
	ds_read_b128 v[100:103], v187 offset:40960
	ds_read_b128 v[104:107], v187 offset:43008
	ds_read_b128 v[108:111], v187 offset:45056
	ds_read_b128 v[192:195], v187 offset:47104
	ds_read_b128 v[196:199], v188 offset:40960
	ds_read_b128 v[200:203], v188 offset:43008
	ds_read_b128 v[204:207], v188 offset:45056
	ds_read_b128 v[208:211], v188 offset:47104
	v_exp_f32_e32 v161, v125
	v_exp_f32_e32 v157, v127
	v_exp_f32_e32 v155, v120
	v_exp_f32_e32 v153, v121
	v_exp_f32_e32 v149, v123
	v_exp_f32_e32 v147, v116
	v_exp_f32_e32 v127, v117
	v_exp_f32_e32 v125, v118
	v_exp_f32_e32 v123, v119
	v_exp_f32_e32 v121, v112
	v_exp_f32_e32 v119, v113
	v_exp_f32_e32 v117, v114
	v_exp_f32_e32 v113, v115
	v_exp_f32_e32 v120, v96
	v_exp_f32_e32 v118, v97
	v_exp_f32_e32 v116, v98
	v_exp_f32_e32 v112, v99
	v_cvt_pk_bf16_f32 v164, v163, v161
	v_cvt_pk_bf16_f32 v165, v159, v157
	v_cvt_pk_bf16_f32 v166, v155, v153
	v_cvt_pk_bf16_f32 v167, v151, v149
	v_cvt_pk_bf16_f32 v168, v147, v127
	v_cvt_pk_bf16_f32 v169, v125, v123
	v_cvt_pk_bf16_f32 v170, v121, v119
	v_cvt_pk_bf16_f32 v171, v117, v113
	v_cvt_pk_bf16_f32 v96, v162, v160
	v_cvt_pk_bf16_f32 v97, v158, v156
	v_cvt_pk_bf16_f32 v98, v154, v152
	v_cvt_pk_bf16_f32 v99, v150, v148
	v_cvt_pk_bf16_f32 v212, v146, v126
	v_cvt_pk_bf16_f32 v213, v124, v122
	v_cvt_pk_bf16_f32 v214, v120, v118
	v_cvt_pk_bf16_f32 v215, v116, v112
	s_setprio 1
	s_waitcnt lgkmcnt(7)
	v_mfma_f32_16x16x32_bf16 v[92:95], v[100:103], v[164:167], v[92:95]
	v_add_f32_e32 v226, 0, v162
	v_add_f32_e32 v227, 0, v163
	v_mfma_f32_16x16x32_bf16 v[88:91], v[100:103], v[96:99], v[88:91]
	v_add_f32_e32 v226, v160, v226
	v_add_f32_e32 v227, v161, v227
	s_waitcnt lgkmcnt(6)
	v_mfma_f32_16x16x32_bf16 v[84:87], v[104:107], v[164:167], v[84:87]
	v_add_f32_e32 v226, v158, v226
	v_add_f32_e32 v227, v159, v227
	v_mfma_f32_16x16x32_bf16 v[80:83], v[104:107], v[96:99], v[80:83]
	v_add_f32_e32 v226, v156, v226
	v_add_f32_e32 v227, v157, v227
	s_waitcnt lgkmcnt(5)
	v_mfma_f32_16x16x32_bf16 v[100:103], v[108:111], v[164:167], v[76:79]
	v_add_f32_e32 v226, v154, v226
	v_add_f32_e32 v227, v155, v227
	v_mfma_f32_16x16x32_bf16 v[104:107], v[108:111], v[96:99], v[72:75]
	v_add_f32_e32 v226, v152, v226
	v_add_f32_e32 v227, v153, v227
	s_waitcnt lgkmcnt(4)
	v_mfma_f32_16x16x32_bf16 v[108:111], v[192:195], v[164:167], v[68:71]
	v_add_f32_e32 v226, v150, v226
	v_add_f32_e32 v227, v151, v227
	v_mfma_f32_16x16x32_bf16 v[64:67], v[192:195], v[96:99], v[64:67]
	v_add_f32_e32 v226, v148, v226
	v_add_f32_e32 v227, v149, v227
	s_waitcnt lgkmcnt(3)
	v_mfma_f32_16x16x32_bf16 v[92:95], v[196:199], v[168:171], v[92:95]
	v_add_f32_e32 v226, v146, v226
	v_add_f32_e32 v227, v147, v227
	v_mfma_f32_16x16x32_bf16 v[76:79], v[196:199], v[212:215], v[88:91]
	v_add_f32_e32 v226, v126, v226
	v_add_f32_e32 v227, v127, v227
	s_waitcnt lgkmcnt(2)
	v_mfma_f32_16x16x32_bf16 v[88:91], v[200:203], v[168:171], v[84:87]
	v_add_f32_e32 v226, v124, v226
	v_add_f32_e32 v227, v125, v227
	v_mfma_f32_16x16x32_bf16 v[72:75], v[200:203], v[212:215], v[80:83]
	v_add_f32_e32 v226, v122, v226
	v_add_f32_e32 v227, v123, v227
	s_waitcnt lgkmcnt(1)
	v_mfma_f32_16x16x32_bf16 v[84:87], v[204:207], v[168:171], v[100:103]
	v_add_f32_e32 v226, v120, v226
	v_add_f32_e32 v227, v121, v227
	v_mfma_f32_16x16x32_bf16 v[68:71], v[204:207], v[212:215], v[104:107]
	v_add_f32_e32 v226, v118, v226
	v_add_f32_e32 v227, v119, v227
	s_waitcnt lgkmcnt(0)
	v_mfma_f32_16x16x32_bf16 v[80:83], v[208:211], v[168:171], v[108:111]
	v_add_f32_e32 v226, v116, v226
	v_add_f32_e32 v227, v117, v227
	v_mfma_f32_16x16x32_bf16 v[64:67], v[208:211], v[212:215], v[64:67]
	v_add_f32_e32 v226, v112, v226
	v_add_f32_e32 v227, v113, v227
	s_setprio 0
	v_pk_add_f32 v[144:145], v[144:145], v[226:227]
	s_andn2_b64 vcc, exec, s[50:51]
	s_cbranch_vccnz .LBB0_375
	ds_write_b128 v179, v[24:27]
	ds_write_b128 v180, v[28:31]
	ds_write_b128 v181, v[32:35]
	ds_write_b128 v182, v[36:39] offset:16384
	ds_write_b128 v183, v[40:43] offset:16384
	s_branch .LBB0_375

; __global__ void __launch_bounds__(256, 2) mega(Params p) {
;   __shared__ __attribute__((aligned(16))) char smem[73728];
	.amdhsa_kernel _Z4mega6Params
		.amdhsa_group_segment_fixed_size 73728
		.amdhsa_private_segment_fixed_size 0
		.amdhsa_kernarg_size 424
		.amdhsa_user_sgpr_count 2
		.amdhsa_user_sgpr_dispatch_ptr 0
		.amdhsa_user_sgpr_queue_ptr 0
		.amdhsa_user_sgpr_kernarg_segment_ptr 1
		.amdhsa_user_sgpr_dispatch_id 0
		.amdhsa_user_sgpr_kernarg_preload_length 0
		.amdhsa_user_sgpr_kernarg_preload_offset 0
		.amdhsa_user_sgpr_private_segment_size 0
		.amdhsa_uses_dynamic_stack 0
		.amdhsa_enable_private_segment 0
		.amdhsa_system_sgpr_workgroup_id_x 1
		.amdhsa_system_sgpr_workgroup_id_y 0
		.amdhsa_system_sgpr_workgroup_id_z 0
		.amdhsa_system_sgpr_workgroup_info 0
		.amdhsa_system_vgpr_workitem_id 2
		.amdhsa_next_free_vgpr 228
		.amdhsa_next_free_sgpr 100
		.amdhsa_accum_offset 228
		.amdhsa_reserve_vcc 1
		.amdhsa_float_round_mode_32 0
		.amdhsa_float_round_mode_16_64 0
		.amdhsa_float_denorm_mode_32 3
		.amdhsa_float_denorm_mode_16_64 3
		.amdhsa_dx10_clamp 1
		.amdhsa_ieee_mode 1
		.amdhsa_fp16_overflow 0
		.amdhsa_tg_split 0
		.amdhsa_exception_fp_ieee_invalid_op 0
		.amdhsa_exception_fp_denorm_src 0
		.amdhsa_exception_fp_ieee_div_zero 0
		.amdhsa_exception_fp_ieee_overflow 0
		.amdhsa_exception_fp_ieee_underflow 0
		.amdhsa_exception_fp_ieee_inexact 0
		.amdhsa_exception_int_div_zero 0
	.end_amdhsa_kernel

; __global__ void __launch_bounds__(256, 2) mega(Params p) {
;   __shared__ __attribute__((aligned(16))) char smem[73728];
amdhsa.kernels:
  - .agpr_count:     0
    .args:
      - .offset:         0
        .size:           168
        .value_kind:     by_value
      - .offset:         168
        .size:           4
        .value_kind:     hidden_block_count_x
      - .offset:         172
        .size:           4
        .value_kind:     hidden_block_count_y
      - .offset:         176
        .size:           4
        .value_kind:     hidden_block_count_z
      - .offset:         180
        .size:           2
        .value_kind:     hidden_group_size_x
      - .offset:         182
        .size:           2
        .value_kind:     hidden_group_size_y
      - .offset:         184
        .size:           2
        .value_kind:     hidden_group_size_z
      - .offset:         186
        .size:           2
        .value_kind:     hidden_remainder_x
      - .offset:         188
        .size:           2
        .value_kind:     hidden_remainder_y
      - .offset:         190
        .size:           2
        .value_kind:     hidden_remainder_z
      - .offset:         208
        .size:           8
        .value_kind:     hidden_global_offset_x
      - .offset:         216
        .size:           8
        .value_kind:     hidden_global_offset_y
      - .offset:         224
        .size:           8
        .value_kind:     hidden_global_offset_z
      - .offset:         232
        .size:           2
        .value_kind:     hidden_grid_dims
      - .offset:         256
        .size:           8
        .value_kind:     hidden_multigrid_sync_arg
    .group_segment_fixed_size: 73728
    .kernarg_segment_align: 8
    .kernarg_segment_size: 424
    .language:       OpenCL C
    .language_version:
      - 2
      - 0
    .max_flat_workgroup_size: 256
    .name:           _Z4mega6Params
    .private_segment_fixed_size: 0
    .sgpr_count:     106
    .sgpr_spill_count: 35
    .symbol:         _Z4mega6Params.kd
    .uniform_work_group_size: 1
    .uses_dynamic_stack: false
    .vgpr_count:     228
    .vgpr_spill_count: 0
    .wavefront_size: 64
